# FFN-up epilogue conv weights prefetched across the LDS barrier / previous pass
# baseline (speedup 1.0000x reference)
; #define LAS __attribute__((address_space(3)))
; DI f32x16 mfma32(bf16x8 a, bf16x8 b, f32x16 c) { return __builtin_amdgcn_mfma_f32_32x32x16_bf16(a, b, c, 0, 0, 0); }
;     ...
;   for (int kt = 0; kt < nk; ++kt) {
;     const int kn = (kt + 2 < nk) ? (kt + 2) : (nk - 1);
;     const LAS char* cur = lds + s0;
;     bf16x8 af[2][2], bfr[2][4];
; #pragma unroll
;     for (int kk = 0; kk < 2; ++kk) {
;       const int xo = kk ? x1 : x0;
;       af[kk][0] = *(const LAS bf16x8*)(cur + a_rd + xo);
;       bfr[kk][0] = *(const LAS bf16x8*)(cur + b_rd + xo);
;       bfr[kk][1] = *(const LAS bf16x8*)(cur + b_rd + 2048 + xo);
;       af[kk][1] = *(const LAS bf16x8*)(cur + a_rd + 2048 + xo);
;       bfr[kk][2] = *(const LAS bf16x8*)(cur + b_rd + 4096 + xo);
;       bfr[kk][3] = *(const LAS bf16x8*)(cur + b_rd + 6144 + xo);
;     }
;     DMA_STEP_(kn, s2);
; #pragma unroll
;     for (int kk = 0; kk < 2; ++kk) {
;       acc[0][0] = mfma32(bfr[kk][0], af[kk][0], acc[0][0]); acc[0][1] = mfma32(bfr[kk][1], af[kk][0], acc[0][1]);
;       acc[1][0] = mfma32(bfr[kk][0], af[kk][1], acc[1][0]); acc[1][1] = mfma32(bfr[kk][1], af[kk][1], acc[1][1]);
;       acc[0][2] = mfma32(bfr[kk][2], af[kk][0], acc[0][2]); acc[0][3] = mfma32(bfr[kk][3], af[kk][0], acc[0][3]);
;       acc[1][2] = mfma32(bfr[kk][2], af[kk][1], acc[1][2]); acc[1][3] = mfma32(bfr[kk][3], af[kk][1], acc[1][3]);
;     }
;     __builtin_amdgcn_sched_group_barrier(0x100, 12, 0);
;     __builtin_amdgcn_sched_group_barrier(0x010, 6, 0);
;     __builtin_amdgcn_sched_group_barrier(0x008, 16, 0);
;     asm volatile("s_waitcnt vmcnt(6) lgkmcnt(0)" ::: "memory");
;     __builtin_amdgcn_s_barrier();
;     asm volatile("" ::: "memory");
;     s0 = (s0 == 2 * STG) ? 0 : s0 + STG;
;     s2 = (s2 == 2 * STG) ? 0 : s2 + STG;
;   }
.LBB0_272:
	s_add_i32 s11, s28, 16
	s_mov_b32 s10, s21
	v_add_u32_e32 v142, s11, v218
	v_add_u32_e32 v150, s11, v0
	s_min_u32 s10, s10, 29
	v_add_u32_e32 v142, v142, v220
	v_add_u32_e32 v150, v150, v220
	s_lshl_b32 s70, s10, 6
	ds_read_b128 v[138:141], v142
	ds_read_b128 v[162:165], v150 offset:8192
	ds_read_b128 v[166:169], v150 offset:10240
	ds_read_b128 v[142:145], v142 offset:2048
	ds_read_b128 v[146:149], v150 offset:12288
	ds_read_b128 v[150:153], v150 offset:14336
	s_mul_i32 vcc_lo, s70, 0x12000
	s_add_i32 s10, s20, s23
	v_lshl_add_u64 v[222:223], v[192:193], 0, vcc
	s_mov_b32 m0, s10
	s_mul_i32 s100, s70, 0x1600
	v_lshl_add_u64 v[224:225], v[194:195], 0, s[100:101]
	s_add_i32 s10, s19, s23
	s_waitcnt lgkmcnt(6)
	v_mfma_f32_32x32x16_bf16 v[66:81], v[182:185], v[154:157], v[66:81]
	global_load_lds_dwordx4 v[222:223], off
	v_mfma_f32_32x32x16_bf16 v[82:97], v[178:181], v[154:157], v[82:97]
	global_load_lds_dwordx4 v[222:223], off offset:1024
	s_add_i32 m0, s10, 0x2000
	v_mfma_f32_32x32x16_bf16 v[18:33], v[182:185], v[158:161], v[18:33]
	global_load_lds_dwordx4 v[224:225], off
	v_mfma_f32_32x32x16_bf16 v[2:17], v[178:181], v[158:161], v[2:17]
	global_load_lds_dwordx4 v[224:225], off offset:1024
	v_mfma_f32_32x32x16_bf16 v[114:129], v[174:177], v[154:157], v[114:129]
	global_load_lds_dwordx4 v[224:225], off offset:2048
	v_mfma_f32_32x32x16_bf16 v[98:113], v[170:173], v[154:157], v[98:113]
	global_load_lds_dwordx4 v[224:225], off offset:3072
	v_mfma_f32_32x32x16_bf16 v[50:65], v[174:177], v[158:161], v[50:65]
	s_add_i32 s10, s28, 0x6000
	s_cmpk_lg_u32 s28, 0xc000
	s_cselect_b32 s28, s10, 0
	s_add_i32 s10, s23, 0x6000
	s_cmpk_lg_u32 s23, 0xc000
	s_cselect_b32 s23, s10, 0
	v_mfma_f32_32x32x16_bf16 v[34:49], v[170:173], v[158:161], v[34:49]
	s_add_i32 s11, s28, 16
	s_waitcnt vmcnt(6) lgkmcnt(0)
	s_barrier
	v_add_u32_e32 v158, s11, v218
	v_add_u32_e32 v170, s11, v0
	v_add_u32_e32 v158, v158, v219
	v_add_u32_e32 v170, v170, v219
	ds_read_b128 v[154:157], v158
	ds_read_b128 v[182:185], v170 offset:8192
	ds_read_b128 v[178:181], v170 offset:10240
	ds_read_b128 v[158:161], v158 offset:2048
	ds_read_b128 v[174:177], v170 offset:12288
	ds_read_b128 v[170:173], v170 offset:14336
	v_mfma_f32_32x32x16_bf16 v[66:81], v[162:165], v[138:141], v[66:81]
	v_mfma_f32_32x32x16_bf16 v[82:97], v[166:169], v[138:141], v[82:97]
	v_mfma_f32_32x32x16_bf16 v[18:33], v[162:165], v[142:145], v[18:33]
	v_mfma_f32_32x32x16_bf16 v[2:17], v[166:169], v[142:145], v[2:17]
	v_mfma_f32_32x32x16_bf16 v[114:129], v[146:149], v[138:141], v[114:129]
	v_mfma_f32_32x32x16_bf16 v[98:113], v[150:153], v[138:141], v[98:113]
	v_mfma_f32_32x32x16_bf16 v[50:65], v[146:149], v[142:145], v[50:65]
	v_mfma_f32_32x32x16_bf16 v[34:49], v[150:153], v[142:145], v[34:49]
	s_add_i32 s11, s28, 16
	s_add_i32 s10, s21, 1
	v_add_u32_e32 v142, s11, v218
	v_add_u32_e32 v150, s11, v0
	s_min_u32 s10, s10, 29
	v_add_u32_e32 v142, v142, v220
	v_add_u32_e32 v150, v150, v220
	s_lshl_b32 s70, s10, 6
	ds_read_b128 v[138:141], v142
	ds_read_b128 v[162:165], v150 offset:8192
	ds_read_b128 v[166:169], v150 offset:10240
	ds_read_b128 v[142:145], v142 offset:2048
	ds_read_b128 v[146:149], v150 offset:12288
	ds_read_b128 v[150:153], v150 offset:14336
	s_mul_i32 vcc_lo, s70, 0x12000
	s_add_i32 s10, s20, s23
	v_lshl_add_u64 v[222:223], v[192:193], 0, vcc
	s_mov_b32 m0, s10
	s_mul_i32 s100, s70, 0x1600
	v_lshl_add_u64 v[224:225], v[194:195], 0, s[100:101]
	s_add_i32 s10, s19, s23
	s_waitcnt lgkmcnt(6)
	v_mfma_f32_32x32x16_bf16 v[66:81], v[182:185], v[154:157], v[66:81]
	global_load_lds_dwordx4 v[222:223], off
	v_mfma_f32_32x32x16_bf16 v[82:97], v[178:181], v[154:157], v[82:97]
	global_load_lds_dwordx4 v[222:223], off offset:1024
	s_add_i32 m0, s10, 0x2000
	v_mfma_f32_32x32x16_bf16 v[18:33], v[182:185], v[158:161], v[18:33]
	global_load_lds_dwordx4 v[224:225], off
	v_mfma_f32_32x32x16_bf16 v[2:17], v[178:181], v[158:161], v[2:17]
	global_load_lds_dwordx4 v[224:225], off offset:1024
	v_mfma_f32_32x32x16_bf16 v[114:129], v[174:177], v[154:157], v[114:129]
	global_load_lds_dwordx4 v[224:225], off offset:2048
	v_mfma_f32_32x32x16_bf16 v[98:113], v[170:173], v[154:157], v[98:113]
	global_load_lds_dwordx4 v[224:225], off offset:3072
	v_mfma_f32_32x32x16_bf16 v[50:65], v[174:177], v[158:161], v[50:65]
	s_add_i32 s10, s28, 0x6000
	s_cmpk_lg_u32 s28, 0xc000
	s_cselect_b32 s28, s10, 0
	s_add_i32 s10, s23, 0x6000
	s_cmpk_lg_u32 s23, 0xc000
	s_cselect_b32 s23, s10, 0
	v_mfma_f32_32x32x16_bf16 v[34:49], v[170:173], v[158:161], v[34:49]
	s_add_i32 s11, s28, 16
	s_waitcnt vmcnt(6) lgkmcnt(0)
	s_barrier
	v_add_u32_e32 v158, s11, v218
	v_add_u32_e32 v170, s11, v0
	v_add_u32_e32 v158, v158, v219
	v_add_u32_e32 v170, v170, v219
	ds_read_b128 v[154:157], v158
	ds_read_b128 v[182:185], v170 offset:8192
	ds_read_b128 v[178:181], v170 offset:10240
	ds_read_b128 v[158:161], v158 offset:2048
	ds_read_b128 v[174:177], v170 offset:12288
	ds_read_b128 v[170:173], v170 offset:14336
	v_mfma_f32_32x32x16_bf16 v[66:81], v[162:165], v[138:141], v[66:81]
	v_mfma_f32_32x32x16_bf16 v[82:97], v[166:169], v[138:141], v[82:97]
	v_mfma_f32_32x32x16_bf16 v[18:33], v[162:165], v[142:145], v[18:33]
	v_mfma_f32_32x32x16_bf16 v[2:17], v[166:169], v[142:145], v[2:17]
	v_mfma_f32_32x32x16_bf16 v[114:129], v[146:149], v[138:141], v[114:129]
	v_mfma_f32_32x32x16_bf16 v[98:113], v[150:153], v[138:141], v[98:113]
	v_mfma_f32_32x32x16_bf16 v[50:65], v[146:149], v[142:145], v[50:65]
	v_mfma_f32_32x32x16_bf16 v[34:49], v[150:153], v[142:145], v[34:49]
	s_add_i32 s21, s21, 2
	s_cmp_eq_u32 s21, 32
	s_cbranch_scc0 .LBB0_272
; #define GAS __attribute__((address_space(1)))
; DI unsigned pk2(float a, float b) { f32x2 v = {a, b}; bf2_t r = __builtin_convertvector(v, bf2_t); return __builtin_bit_cast(unsigned, r); }
;     ...
;   {
;     const int h = lane >> 5, cl = lane & 31;
; #pragma unroll
;     for (int i = 0; i < 2; ++i)
; #pragma unroll
;       for (int j = 0; j < 4; ++j)
; #pragma unroll
;         for (int g = 0; g < 4; ++g) {
;           u32x2 w; w.x = pk2(acc[i][j][4 * g], acc[i][j][4 * g + 1]); w.y = pk2(acc[i][j][4 * g + 2], acc[i][j][4 * g + 3]);
;           *(u32x2*)(smem + (wr * 64 + i * 32 + cl) * 528 + (wc * 128 + j * 32 + 8 * g + 4 * h) * 2) = w;
;         }
;   }
;   __syncthreads();
;     ...
;       const int j8 = (tid2 & 7) * 8;
;       const int ja0 = (nt * 2 + p) * 64, ja = ja0 + j8;
;       f32x4 wa[4][2], wg[4][2];
; #pragma unroll
;       for (int hh = 0; hh < 2; ++hh) {
;         wa[0][hh] = *(const GAS f32x4*)(cw + ja + 4 * hh); wa[1][hh] = *(const GAS f32x4*)(cw + 5632 + ja + 4 * hh); wa[2][hh] = *(const GAS f32x4*)(cw + 11264 + ja + 4 * hh); wa[3][hh] = *(const GAS f32x4*)(cb + ja + 4 * hh);
;         wg[0][hh] = *(const GAS f32x4*)(cw + 2816 + ja + 4 * hh); wg[1][hh] = *(const GAS f32x4*)(cw + 5632 + 2816 + ja + 4 * hh); wg[2][hh] = *(const GAS f32x4*)(cw + 11264 + 2816 + ja + 4 * hh); wg[3][hh] = *(const GAS f32x4*)(cb + 2816 + ja + 4 * hh);
;       }
	s_waitcnt lgkmcnt(0)
	v_mul_lo_u32 v0, v197, s55
	v_add_u32_e32 v0, 16, v0
	s_nop 1
	v_cvt_pk_bf16_f32 v66, v66, v67
	v_cvt_pk_bf16_f32 v67, v68, v69
	v_lshlrev_b32_e32 v68, 3, v196
	s_lshl_b32 s10, s18, 1
	v_add3_u32 v0, v0, v68, s10
	v_cvt_pk_bf16_f32 v68, v70, v71
	v_cvt_pk_bf16_f32 v69, v72, v73
	s_waitcnt vmcnt(0)
	s_barrier
	ds_write2_b64 v0, v[66:67], v[68:69] offset1:2
	v_cvt_pk_bf16_f32 v66, v74, v75
	v_cvt_pk_bf16_f32 v67, v76, v77
	v_cvt_pk_bf16_f32 v68, v78, v79
	v_cvt_pk_bf16_f32 v69, v80, v81
	ds_write2_b64 v0, v[66:67], v[68:69] offset0:4 offset1:6
	v_cvt_pk_bf16_f32 v66, v82, v83
	v_cvt_pk_bf16_f32 v67, v84, v85
	v_cvt_pk_bf16_f32 v68, v86, v87
	v_cvt_pk_bf16_f32 v69, v88, v89
	ds_write2_b64 v0, v[66:67], v[68:69] offset0:8 offset1:10
	v_cvt_pk_bf16_f32 v66, v90, v91
	v_cvt_pk_bf16_f32 v67, v92, v93
	v_cvt_pk_bf16_f32 v68, v94, v95
	v_cvt_pk_bf16_f32 v69, v96, v97
	ds_write2_b64 v0, v[66:67], v[68:69] offset0:12 offset1:14
	v_cvt_pk_bf16_f32 v66, v114, v115
	v_cvt_pk_bf16_f32 v67, v116, v117
	v_cvt_pk_bf16_f32 v68, v118, v119
	v_cvt_pk_bf16_f32 v69, v120, v121
	ds_write2_b64 v0, v[66:67], v[68:69] offset0:16 offset1:18
	v_cvt_pk_bf16_f32 v66, v122, v123
	v_cvt_pk_bf16_f32 v67, v124, v125
	v_cvt_pk_bf16_f32 v68, v126, v127
	v_cvt_pk_bf16_f32 v69, v128, v129
	ds_write2_b64 v0, v[66:67], v[68:69] offset0:20 offset1:22
	v_cvt_pk_bf16_f32 v66, v98, v99
	v_cvt_pk_bf16_f32 v67, v100, v101
	v_cvt_pk_bf16_f32 v68, v102, v103
	v_cvt_pk_bf16_f32 v69, v104, v105
	ds_write2_b64 v0, v[66:67], v[68:69] offset0:24 offset1:26
	v_cvt_pk_bf16_f32 v66, v106, v107
	v_cvt_pk_bf16_f32 v67, v108, v109
	v_cvt_pk_bf16_f32 v68, v110, v111
	v_cvt_pk_bf16_f32 v69, v112, v113
	ds_write2_b64 v0, v[66:67], v[68:69] offset0:28 offset1:30
	v_add_u32_e32 v0, 0x4000, v0
	v_lshlrev_b32_e32 v178, 3, v189
	v_and_b32_e32 v178, 56, v178
	s_mul_i32 s100, s22, 0x80
	v_or_b32_e32 v178, s100, v178
	v_mov_b32_e32 v179, 0
	v_lshlrev_b64 v[178:179], 2, v[178:179]
	v_lshl_add_u64 v[108:109], s[12:13], 0, v[178:179]
	v_lshl_add_u64 v[116:117], s[52:53], 0, v[178:179]
	v_lshl_add_u64 v[124:125], s[56:57], 0, v[178:179]
	v_lshl_add_u64 v[142:143], s[16:17], 0, v[178:179]
	v_lshl_add_u64 v[150:151], s[58:59], 0, v[178:179]
	v_lshl_add_u64 v[158:159], s[60:61], 0, v[178:179]
	v_lshl_add_u64 v[166:167], s[62:63], 0, v[178:179]
	v_lshl_add_u64 v[174:175], s[64:65], 0, v[178:179]
	global_load_dwordx4 v[104:107], v[108:109], off
	s_nop 0
	global_load_dwordx4 v[108:111], v[108:109], off offset:16
	global_load_dwordx4 v[112:115], v[116:117], off
	s_nop 0
	global_load_dwordx4 v[116:119], v[116:117], off offset:16
	global_load_dwordx4 v[120:123], v[124:125], off
	s_nop 0
	global_load_dwordx4 v[124:127], v[124:125], off offset:16
	global_load_dwordx4 v[138:141], v[142:143], off
	s_nop 0
	global_load_dwordx4 v[142:145], v[142:143], off offset:16
	global_load_dwordx4 v[146:149], v[150:151], off
	s_nop 0
	global_load_dwordx4 v[150:153], v[150:151], off offset:16
	global_load_dwordx4 v[154:157], v[158:159], off
	s_nop 0
	global_load_dwordx4 v[158:161], v[158:159], off offset:16
	global_load_dwordx4 v[162:165], v[166:167], off
	s_nop 0
	global_load_dwordx4 v[166:169], v[166:167], off offset:16
	global_load_dwordx4 v[170:173], v[174:175], off
	s_nop 0
	global_load_dwordx4 v[174:177], v[174:175], off offset:16
	v_cvt_pk_bf16_f32 v2, v2, v3
	v_cvt_pk_bf16_f32 v3, v4, v5
	v_cvt_pk_bf16_f32 v4, v6, v7
	v_cvt_pk_bf16_f32 v5, v8, v9
	ds_write2_b64 v0, v[2:3], v[4:5] offset0:72 offset1:74
	v_cvt_pk_bf16_f32 v2, v10, v11
	v_cvt_pk_bf16_f32 v3, v12, v13
	v_cvt_pk_bf16_f32 v4, v14, v15
	v_cvt_pk_bf16_f32 v5, v16, v17
	ds_write2_b64 v0, v[2:3], v[4:5] offset0:76 offset1:78
	v_cvt_pk_bf16_f32 v2, v50, v51
	v_cvt_pk_bf16_f32 v3, v52, v53
	v_cvt_pk_bf16_f32 v4, v54, v55
	v_cvt_pk_bf16_f32 v5, v56, v57
	s_cmpk_lt_i32 s15, 0x200
	ds_write2_b64 v0, v[2:3], v[4:5] offset0:80 offset1:82
	v_cvt_pk_bf16_f32 v2, v58, v59
	v_cvt_pk_bf16_f32 v3, v60, v61
	v_cvt_pk_bf16_f32 v4, v62, v63
	v_cvt_pk_bf16_f32 v5, v64, v65
	s_cselect_b32 s10, 0x7ff, s78
	v_cvt_pk_bf16_f32 v18, v18, v19
	v_cvt_pk_bf16_f32 v19, v20, v21
	v_cvt_pk_bf16_f32 v20, v22, v23
	v_cvt_pk_bf16_f32 v21, v24, v25
	ds_write2_b64 v0, v[2:3], v[4:5] offset0:84 offset1:86
	v_cvt_pk_bf16_f32 v2, v34, v35
	v_cvt_pk_bf16_f32 v3, v36, v37
	v_cvt_pk_bf16_f32 v4, v38, v39
	v_cvt_pk_bf16_f32 v5, v40, v41
	s_and_b32 s11, s10, s46
	ds_write2_b64 v0, v[18:19], v[20:21] offset0:64 offset1:66
	v_cvt_pk_bf16_f32 v18, v26, v27
	v_cvt_pk_bf16_f32 v19, v28, v29
	v_cvt_pk_bf16_f32 v20, v30, v31
	v_cvt_pk_bf16_f32 v21, v32, v33
	ds_write2_b64 v0, v[2:3], v[4:5] offset0:88 offset1:90
	v_cvt_pk_bf16_f32 v2, v42, v43
	v_cvt_pk_bf16_f32 v3, v44, v45
	v_cvt_pk_bf16_f32 v4, v46, v47
	v_cvt_pk_bf16_f32 v5, v48, v49
	s_cmp_eq_u32 s11, 0
	ds_write2_b64 v0, v[18:19], v[20:21] offset0:68 offset1:70
	ds_write2_b64 v0, v[2:3], v[4:5] offset0:92 offset1:94
	s_waitcnt lgkmcnt(0)
	s_barrier
	s_cselect_b64 s[18:19], -1, 0
	s_add_i32 s11, s46, 0x80
	v_lshlrev_b32_e32 v0, 3, v189
	s_and_b32 s10, s11, s10
	v_and_b32_e32 v96, 56, v0
	s_cmp_eq_u32 s10, 0
	v_lshlrev_b32_e32 v0, 1, v96
	s_mov_b32 s40, 0
	s_cselect_b64 s[20:21], -1, 0
	s_lshl_b32 s47, s22, 7
	v_add_u32_e32 v97, 16, v0
	v_lshl_add_u64 v[90:91], s[44:45], 0, v[0:1]
	s_mov_b64 s[28:29], -1
	s_branch .LBB0_275

; #define GAS __attribute__((address_space(1)))
;     ...
;     for (int p = 0; p < 2; ++p) {
;       const int j8 = (tid2 & 7) * 8;
;       const int ja0 = (nt * 2 + p) * 64, ja = ja0 + j8;
;       f32x4 wa[4][2], wg[4][2];
; #pragma unroll
;       for (int hh = 0; hh < 2; ++hh) {
;         wa[0][hh] = *(const GAS f32x4*)(cw + ja + 4 * hh); wa[1][hh] = *(const GAS f32x4*)(cw + 5632 + ja + 4 * hh); wa[2][hh] = *(const GAS f32x4*)(cw + 11264 + ja + 4 * hh); wa[3][hh] = *(const GAS f32x4*)(cb + ja + 4 * hh);
;         wg[0][hh] = *(const GAS f32x4*)(cw + 2816 + ja + 4 * hh); wg[1][hh] = *(const GAS f32x4*)(cw + 5632 + 2816 + ja + 4 * hh); wg[2][hh] = *(const GAS f32x4*)(cw + 11264 + 2816 + ja + 4 * hh); wg[3][hh] = *(const GAS f32x4*)(cb + 2816 + ja + 4 * hh);
;       }
.LBB0_275:
	s_lshl_b32 s10, s40, 6
	s_xor_b64 s[22:23], s[28:29], -1
	s_or_b32 s28, s10, s47
	s_cmp_eq_u32 s40, 0
	s_cbranch_scc1 .Lmy_epi_w0
	s_waitcnt vmcnt(4)
	s_branch .Lmy_epi_w1

; #define GAS __attribute__((address_space(1)))
;     ...
;     for (int p = 0; p < 2; ++p) {
;       const int j8 = (tid2 & 7) * 8;
;       const int ja0 = (nt * 2 + p) * 64, ja = ja0 + j8;
;       f32x4 wa[4][2], wg[4][2];
; #pragma unroll
;       for (int hh = 0; hh < 2; ++hh) {
;         wa[0][hh] = *(const GAS f32x4*)(cw + ja + 4 * hh); wa[1][hh] = *(const GAS f32x4*)(cw + 5632 + ja + 4 * hh); wa[2][hh] = *(const GAS f32x4*)(cw + 11264 + ja + 4 * hh); wa[3][hh] = *(const GAS f32x4*)(cb + ja + 4 * hh);
;         wg[0][hh] = *(const GAS f32x4*)(cw + 2816 + ja + 4 * hh); wg[1][hh] = *(const GAS f32x4*)(cw + 5632 + 2816 + ja + 4 * hh); wg[2][hh] = *(const GAS f32x4*)(cw + 11264 + 2816 + ja + 4 * hh); wg[3][hh] = *(const GAS f32x4*)(cb + 2816 + ja + 4 * hh);
;       }
; #pragma unroll 1
;       for (int i = 0; i < 4; ++i) {
;         const int r = (tid2 + 256 * i) >> 3;
.Lmy_epi_w1:
	v_mov_b32_e32 v2, v104
	v_mov_b32_e32 v3, v105
	v_mov_b32_e32 v4, v106
	v_mov_b32_e32 v5, v107
	v_mov_b32_e32 v6, v108
	v_mov_b32_e32 v7, v109
	v_mov_b32_e32 v8, v110
	v_mov_b32_e32 v9, v111
	v_mov_b32_e32 v10, v112
	v_mov_b32_e32 v11, v113
	v_mov_b32_e32 v12, v114
	v_mov_b32_e32 v13, v115
	v_mov_b32_e32 v14, v116
	v_mov_b32_e32 v15, v117
	v_mov_b32_e32 v16, v118
	v_mov_b32_e32 v17, v119
	v_mov_b32_e32 v18, v120
	v_mov_b32_e32 v19, v121
	v_mov_b32_e32 v20, v122
	v_mov_b32_e32 v21, v123
	v_mov_b32_e32 v22, v124
	v_mov_b32_e32 v23, v125
	v_mov_b32_e32 v24, v126
	v_mov_b32_e32 v25, v127
	v_mov_b32_e32 v26, v138
	v_mov_b32_e32 v27, v139
	v_mov_b32_e32 v28, v140
	v_mov_b32_e32 v29, v141
	v_mov_b32_e32 v30, v142
	v_mov_b32_e32 v31, v143
	v_mov_b32_e32 v32, v144
	v_mov_b32_e32 v33, v145
	v_mov_b32_e32 v34, v146
	v_mov_b32_e32 v35, v147
	v_mov_b32_e32 v36, v148
	v_mov_b32_e32 v37, v149
	v_mov_b32_e32 v38, v150
	v_mov_b32_e32 v39, v151
	v_mov_b32_e32 v40, v152
	v_mov_b32_e32 v41, v153
	v_mov_b32_e32 v42, v154
	v_mov_b32_e32 v43, v155
	v_mov_b32_e32 v44, v156
	v_mov_b32_e32 v45, v157
	v_mov_b32_e32 v46, v158
	v_mov_b32_e32 v47, v159
	v_mov_b32_e32 v48, v160
	v_mov_b32_e32 v49, v161
	v_mov_b32_e32 v50, v162
	v_mov_b32_e32 v51, v163
	v_mov_b32_e32 v52, v164
	v_mov_b32_e32 v53, v165
	v_mov_b32_e32 v54, v166
	v_mov_b32_e32 v55, v167
	v_mov_b32_e32 v56, v168
	v_mov_b32_e32 v57, v169
	v_mov_b32_e32 v58, v170
	v_mov_b32_e32 v59, v171
	v_mov_b32_e32 v60, v172
	v_mov_b32_e32 v61, v173
	v_mov_b32_e32 v62, v174
	v_mov_b32_e32 v63, v175
	v_mov_b32_e32 v64, v176
	v_mov_b32_e32 v65, v177
	s_cmp_eq_u32 s40, 0
	s_cbranch_scc0 .Lmy_epi_nopf
	s_or_b32 s100, s47, 64
	v_or_b32_e32 v178, s100, v96
	v_mov_b32_e32 v179, 0
	v_lshlrev_b64 v[178:179], 2, v[178:179]
	v_lshl_add_u64 v[108:109], s[12:13], 0, v[178:179]
	v_lshl_add_u64 v[116:117], s[52:53], 0, v[178:179]
	v_lshl_add_u64 v[124:125], s[56:57], 0, v[178:179]
	v_lshl_add_u64 v[142:143], s[16:17], 0, v[178:179]
	v_lshl_add_u64 v[150:151], s[58:59], 0, v[178:179]
	v_lshl_add_u64 v[158:159], s[60:61], 0, v[178:179]
	v_lshl_add_u64 v[166:167], s[62:63], 0, v[178:179]
	v_lshl_add_u64 v[174:175], s[64:65], 0, v[178:179]
	global_load_dwordx4 v[104:107], v[108:109], off
	s_nop 0
	global_load_dwordx4 v[108:111], v[108:109], off offset:16
	global_load_dwordx4 v[112:115], v[116:117], off
	s_nop 0
	global_load_dwordx4 v[116:119], v[116:117], off offset:16
	global_load_dwordx4 v[120:123], v[124:125], off
	s_nop 0
	global_load_dwordx4 v[124:127], v[124:125], off offset:16
	global_load_dwordx4 v[138:141], v[142:143], off
	s_nop 0
	global_load_dwordx4 v[142:145], v[142:143], off offset:16
	global_load_dwordx4 v[146:149], v[150:151], off
	s_nop 0
	global_load_dwordx4 v[150:153], v[150:151], off offset:16
	global_load_dwordx4 v[154:157], v[158:159], off
	s_nop 0
	global_load_dwordx4 v[158:161], v[158:159], off offset:16
	global_load_dwordx4 v[162:165], v[166:167], off
	s_nop 0
	global_load_dwordx4 v[166:169], v[166:167], off offset:16
	global_load_dwordx4 v[170:173], v[174:175], off
	s_nop 0
	global_load_dwordx4 v[174:177], v[174:175], off offset:16
.Lmy_epi_nopf:
	s_ashr_i32 s29, s28, 31
	v_lshl_add_u32 v0, s40, 8, v97
	v_lshl_add_u64 v[92:93], s[28:29], 1, v[90:91]
	s_mov_b32 s70, 0
	s_branch .LBB0_278
